# S=5, P7b task rebalance (guarded for a 256-workgroup grid), recurrence producer/consumer loop edits
# speedup vs baseline: 1.0032x; 1.0032x over previous
; #define INP(k) karg_in(k)
; #define tid opq((wave << 6) | lane_now())
; __device__ __forceinline__ void rglru_task(const Params& P, LAS unsigned char* lds, int b, int n, int qd, int tid, int t0, int t1) {
;     ...
;     const int cb0 = n * 128, oc0 = cb0 + qd * 32;
;     const bool prompt = b >= 0;
;     for (int i = tid; i < 640; i += NTHR) cw[i] = i < 512 ? INP(15)[(size_t)(i >> 7) * D + cb0 + (i & 127)] : INP(16)[cb0 + (i - 512)];
; __global__ void __launch_bounds__(NTHR, 2) fwd_megakernel(Params P) {
;     ...
;             if (wg < 96) rglru_task(P, lds, -1, (wg - 64) >> 2, (wg - 64) & 3, tid, 0, 1);
.LBB0_1763:
	s_sub_i32 s3, s2, 0x80
	s_cmpk_eq_u32 s78, 0x100
	s_cbranch_scc1 .Lsrg_ok
	s_sub_i32 s3, s2, 64
.Lsrg_ok:
	s_cmpk_gt_u32 s3, 0x1f
	s_cbranch_scc1 .LBB0_1784
	v_mov_b32_e32 v47, v167
	s_load_dwordx2 s[14:15], s[0:1], 0x108
	s_load_dwordx2 s[6:7], s[0:1], 0x108
	s_load_dwordx2 s[8:9], s[0:1], 0x108
	s_lshr_b32 s18, s3, 2
	s_movk_i32 s3, 0x280
	s_lshl_b32 s4, s18, 7
	v_cmp_gt_i32_e32 vcc, s3, v47
	v_lshl_add_u32 v4, v47, 2, 0
	s_and_saveexec_b64 s[10:11], vcc
	s_cbranch_execz .LBB0_1771
	v_and_b32_e32 v0, 0x7f, v47
	s_mov_b32 s5, 0
	s_movk_i32 s3, 0x7f
	v_mov_b32_e32 v1, 0
	v_add_u32_e32 v7, 0xfffffe00, v47
	v_add_u32_e32 v5, 0x15880, v4
	s_mov_b64 s[12:13], 0
	s_movk_i32 s19, 0x1ff
	v_lshlrev_b32_e32 v0, 2, v0
	s_branch .LBB0_1767
